# P2 queue reorder: WGs with (bid>>3)<32 run their narrow forget-logit tile first (de-phase epilogues)
# speedup vs baseline: 1.0047x; 1.0047x over previous
.LBB0_215:
	v_writelane_b32 v250, s86, 14
	s_nop 1
	v_writelane_b32 v250, s87, 15
	v_writelane_b32 v250, s84, 16
	s_nop 1
	v_writelane_b32 v250, s85, 17
	s_or_b64 exec, exec, s[4:5]
	s_ashr_i32 s3, s2, 3
	s_cmpk_gt_i32 s3, 0x222
	v_and_b32_e32 v161, 31, v204
	v_lshrrev_b32_e32 v194, 1, v204
	v_and_b32_e32 v193, 7, v204
	s_waitcnt lgkmcnt(0)
	s_barrier
	s_cbranch_scc1 .LBB0_768
	s_and_b32 s4, s2, 7
	s_xor_b32 s0, s4, 7
	v_readlane_b32 s6, v250, 16
	s_add_i32 s0, s0, s6
	s_ashr_i32 s33, s0, 3
	s_cmp_eq_u32 s4, 0
	s_cselect_b64 s[8:9], -1, 0
	s_and_b64 s[0:1], s[8:9], exec
	v_readlane_b32 s7, v250, 17
	s_cselect_b32 s35, 2, 0
	s_lshl_b32 s43, s4, 5
	s_or_b32 s45, s43, 0xfffffe00
	v_readlane_b32 s6, v250, 0
	v_readlane_b32 s7, v250, 1
	s_add_u32 s10, s6, 0xa64100
	s_addc_u32 s11, s7, 0
	s_add_u32 s12, s6, 0x24100
	v_lshlrev_b32_e32 v152, 11, v192
	v_mov_b32_e32 v153, 0
	s_addc_u32 s13, s7, 0
	v_lshl_add_u64 v[0:1], s[10:11], 0, v[152:153]
	v_and_b32_e32 v2, 0x70, v8
	v_mov_b32_e32 v3, v153
	s_movk_i32 s0, 0x90
	v_lshl_add_u64 v[154:155], v[0:1], 0, v[2:3]
	v_lshl_add_u64 v[0:1], s[12:13], 0, v[152:153]
	v_mad_u32_u24 v178, v192, s0, v2
	s_movk_i32 s0, 0x1c0
	v_lshl_add_u64 v[156:157], v[0:1], 0, v[2:3]
	v_and_or_b32 v0, v194, s0, v161
	s_movk_i32 s0, 0x80
	v_cmp_gt_u32_e32 vcc, 8, v161
	v_cmp_gt_u32_e64 s[0:1], s0, v204
	s_and_b64 s[16:17], s[0:1], vcc
	s_add_u32 s18, s6, 0x15d28100
	s_addc_u32 s19, s7, 0
	s_add_u32 s20, s6, 0xdb84100
	v_mul_u32_u24_e32 v181, 0x90, v0
	v_and_b32_e32 v3, 64, v204
	v_lshlrev_b32_e32 v0, 2, v161
	v_mov_b32_e32 v1, v153
	s_addc_u32 s21, s7, 0
	v_and_b32_e32 v182, 4, v192
	v_lshl_add_u64 v[158:159], s[24:25], 0, v[0:1]
	v_or_b32_e32 v0, 16, v3
	s_add_u32 s22, s6, 0x12ca8100
	v_lshrrev_b32_e32 v185, 4, v0
	v_or_b32_e32 v186, v0, v182
	v_or_b32_e32 v0, 24, v3
	s_addc_u32 s23, s7, 0
	v_lshrrev_b32_e32 v187, 4, v0
	v_or_b32_e32 v188, v0, v182
	v_or_b32_e32 v0, 32, v3
	s_add_u32 s24, s6, 0x14ca8100
	v_lshrrev_b32_e32 v190, 4, v0
	v_or_b32_e32 v191, v0, v182
	v_or_b32_e32 v0, 40, v3
	s_addc_u32 s25, s7, 0
	v_lshrrev_b32_e32 v195, 4, v0
	v_or_b32_e32 v196, v0, v182
	v_or_b32_e32 v0, 48, v3
	s_add_u32 s36, s6, 0x18dac100
	v_lshrrev_b32_e32 v197, 4, v0
	v_or_b32_e32 v198, v0, v182
	v_or_b32_e32 v0, 56, v3
	s_addc_u32 s37, s7, 0
	v_lshrrev_b32_e32 v199, 4, v0
	v_or_b32_e32 v200, v0, v182
	v_lshrrev_b32_e32 v0, 2, v204
	s_add_u32 s47, s6, 0x4aa4100
	v_and_b32_e32 v162, 24, v160
	v_mul_u32_u24_e32 v1, 0x50, v0
	s_addc_u32 s49, s7, 0
	v_lshl_add_u32 v201, v162, 1, v1
	v_and_b32_e32 v1, 0x39f, v204
	s_add_u32 s38, s6, 0xab04100
	v_mul_u32_u24_e32 v203, 0x50, v1
	s_addc_u32 s39, s7, 0
	v_and_b32_e32 v1, 3, v204
	s_add_u32 s40, s6, 0xcb04100
	v_lshl_or_b32 v152, v193, 4, v152
	v_lshlrev_b32_e32 v1, 4, v1
	v_and_b32_e32 v2, 0x5f, v204
	s_addc_u32 s41, s7, 0
	s_lshl_b32 s0, s4, 1
	v_lshl_add_u64 v[166:167], s[6:7], 0, v[152:153]
	v_lshl_or_b32 v152, v0, 11, v1
	v_mul_u32_u24_e32 v179, 0x90, v2
	v_and_b32_e32 v180, 16, v194
	v_and_b32_e32 v183, 4, v11
	v_or_b32_e32 v184, v182, v3
	v_or_b32_e32 v189, 8, v182
	v_lshlrev_b32_e32 v164, 10, v0
	v_mul_u32_u24_e32 v202, 0x50, v2
	s_or_b32 s51, s0, 0xffffde00
	v_lshl_add_u64 v[168:169], s[6:7], 0, v[152:153]
	s_mov_b32 s57, 0x18200000
	s_mov_b32 s88, 0xbfb8aa3b
	s_mov_b32 s89, 0x3f2aaaab
	s_mov_b32 s42, 0x3ecc95a3
	s_mov_b32 s44, 0x3e9b6dac
	s_mov_b32 s46, 0x3f2aaada
	s_mov_b32 s48, 0x3f317218
	s_mov_b32 s50, 0xb102e308
	s_mov_b32 s90, 0x7f800000
	s_mov_b32 s91, 0x33800000
	s_movk_i32 s92, 0x2100
	s_movk_i32 s95, 0x840
	s_mov_b32 s96, 0x12c88100
	s_mov_b32 s56, 0x3e38aa3b
	s_mov_b64 s[58:59], 0x10000
	s_mov_b32 s97, 0x18180000
	s_mov_b64 s[60:61], 0x4aa4500
	s_mov_b64 s[64:65], 0x4ab4500
	s_mov_b32 s93, 0xaae4100
	s_movk_i32 s94, 0x1080
	s_mov_b64 s[66:67], 0x17d29100
	s_mov_b64 s[72:73], 0xfb85100
	v_mov_b32_e32 v205, 0x7f800000
	v_mov_b32_e32 v206, 0x7fc00000
	v_mov_b32_e32 v207, 0xff800000
	v_mbcnt_hi_u32_b32 v208, -1, v163
	s_mov_b32 s98, 0
	s_movk_i32 s99, 0x222
	s_cmp_lt_i32 s3, 32
	s_cbranch_scc0 .Lp2_noreorder
	s_add_i32 s3, s3, 0x200
	s_mov_b32 s98, 1
.Lp2_noreorder:
	s_branch .LBB0_219
.LBB0_217:
	v_lshlrev_b32_e32 v152, 1, v55
	v_lshl_add_u64 v[4:5], v[4:5], 0, v[152:153]
	global_store_dwordx4 v[4:5], v[0:3], off
.LBB0_218:
	v_readlane_b32 s4, v250, 10
	v_readlane_b32 s6, v250, 12
	v_readlane_b32 s7, v250, 13
	s_mov_b64 s[62:63], s[6:7]
	v_readlane_b32 s5, v250, 11
	s_cmp_eq_u32 s98, 1
	s_cbranch_scc1 .Lp2_first_done
	s_add_i32 s3, s3, s33
	s_cmp_gt_i32 s3, s99
	s_cbranch_scc1 .LBB0_768
	s_branch .LBB0_219
.Lp2_first_done:
	s_sub_i32 s3, s3, 0x200
	s_mov_b32 s98, 2
	s_movk_i32 s99, 0x1ff

	.amdhsa_kernel _Z4megaILin1EEv6Params
		.amdhsa_group_segment_fixed_size 73748
		.amdhsa_private_segment_fixed_size 0
		.amdhsa_kernarg_size 440
		.amdhsa_user_sgpr_count 2
		.amdhsa_user_sgpr_dispatch_ptr 0
		.amdhsa_user_sgpr_queue_ptr 0
		.amdhsa_user_sgpr_kernarg_segment_ptr 1
		.amdhsa_user_sgpr_dispatch_id 0
		.amdhsa_user_sgpr_kernarg_preload_length 0
		.amdhsa_user_sgpr_kernarg_preload_offset 0
		.amdhsa_user_sgpr_private_segment_size 0
		.amdhsa_uses_dynamic_stack 0
		.amdhsa_enable_private_segment 0
		.amdhsa_system_sgpr_workgroup_id_x 1
		.amdhsa_system_sgpr_workgroup_id_y 0
		.amdhsa_system_sgpr_workgroup_id_z 0
		.amdhsa_system_sgpr_workgroup_info 0
		.amdhsa_system_vgpr_workitem_id 2
		.amdhsa_next_free_vgpr 251
		.amdhsa_next_free_sgpr 100
		.amdhsa_accum_offset 252
		.amdhsa_reserve_vcc 1
		.amdhsa_float_round_mode_32 0
		.amdhsa_float_round_mode_16_64 0
		.amdhsa_float_denorm_mode_32 3
		.amdhsa_float_denorm_mode_16_64 3
		.amdhsa_dx10_clamp 1
		.amdhsa_ieee_mode 1
		.amdhsa_fp16_overflow 0
		.amdhsa_tg_split 0
		.amdhsa_exception_fp_ieee_invalid_op 0
		.amdhsa_exception_fp_denorm_src 0
		.amdhsa_exception_fp_ieee_div_zero 0
		.amdhsa_exception_fp_ieee_overflow 0
		.amdhsa_exception_fp_ieee_underflow 0
		.amdhsa_exception_fp_ieee_inexact 0
		.amdhsa_exception_int_div_zero 0
	.end_amdhsa_kernel

.Lfunc_end0:
	.size	_Z4megaILin1EEv6Params, .Lfunc_end0-_Z4megaILin1EEv6Params
	.set _Z4megaILin1EEv6Params.num_vgpr, 251
	.set _Z4megaILin1EEv6Params.num_agpr, 0
	.set _Z4megaILin1EEv6Params.numbered_sgpr, 100
	.set _Z4megaILin1EEv6Params.num_named_barrier, 0
	.set _Z4megaILin1EEv6Params.private_seg_size, 0
	.set _Z4megaILin1EEv6Params.uses_vcc, 1
	.set _Z4megaILin1EEv6Params.uses_flat_scratch, 0
	.set _Z4megaILin1EEv6Params.has_dyn_sized_stack, 0
	.set _Z4megaILin1EEv6Params.has_recursion, 0
	.set _Z4megaILin1EEv6Params.has_indirect_call, 0

amdhsa.kernels:
  - .agpr_count:     0
    .args:
      - .offset:         0
        .size:           184
        .value_kind:     by_value
      - .offset:         184
        .size:           4
        .value_kind:     hidden_block_count_x
      - .offset:         188
        .size:           4
        .value_kind:     hidden_block_count_y
      - .offset:         192
        .size:           4
        .value_kind:     hidden_block_count_z
      - .offset:         196
        .size:           2
        .value_kind:     hidden_group_size_x
      - .offset:         198
        .size:           2
        .value_kind:     hidden_group_size_y
      - .offset:         200
        .size:           2
        .value_kind:     hidden_group_size_z
      - .offset:         202
        .size:           2
        .value_kind:     hidden_remainder_x
      - .offset:         204
        .size:           2
        .value_kind:     hidden_remainder_y
      - .offset:         206
        .size:           2
        .value_kind:     hidden_remainder_z
      - .offset:         224
        .size:           8
        .value_kind:     hidden_global_offset_x
      - .offset:         232
        .size:           8
        .value_kind:     hidden_global_offset_y
      - .offset:         240
        .size:           8
        .value_kind:     hidden_global_offset_z
      - .offset:         248
        .size:           2
        .value_kind:     hidden_grid_dims
      - .offset:         272
        .size:           8
        .value_kind:     hidden_multigrid_sync_arg
    .group_segment_fixed_size: 73748
    .kernarg_segment_align: 8
    .kernarg_segment_size: 440
    .language:       OpenCL C
    .language_version:
      - 2
      - 0
    .max_flat_workgroup_size: 256
    .name:           _Z4megaILin1EEv6Params
    .private_segment_fixed_size: 0
    .sgpr_count:     106
    .sgpr_spill_count: 20
    .symbol:         _Z4megaILin1EEv6Params.kd
    .uniform_work_group_size: 1
    .uses_dynamic_stack: false
    .vgpr_count:     251
    .vgpr_spill_count: 0
    .wavefront_size: 64
